# local/group seams: L1 invalidate issued right after the arrival, overlapping the poll
# speedup vs baseline: 1.0159x; 1.0033x over previous
; __device__ __forceinline__ unsigned xb_ld(unsigned* p)              { return __hip_atomic_load(p, __ATOMIC_RELAXED, __HIP_MEMORY_SCOPE_AGENT); }
; __device__ __forceinline__ unsigned xb_add(unsigned* p, unsigned v) { return __hip_atomic_fetch_add(p, v, __ATOMIC_RELAXED, __HIP_MEMORY_SCOPE_AGENT); }
; #define XB_SPIN(cond, bar) do { unsigned _sp = 0; while (cond) { __builtin_amdgcn_s_sleep(8); \
;     if ((++_sp & 255u) == 0u) { if (xb_ld(&(bar)[XB_TMO])) break; if (_sp > XB_SPIN_CAP) { atomicAdd(&(bar)[XB_TMO], 1u); break; } } } } while (0)
; __device__ __forceinline__ void xcd_barrier(const XcdBarrier& b) {
;     asm volatile("s_waitcnt vmcnt(0)" ::: "memory");
;     __syncthreads();
;     if (threadIdx.x == 0) {
;         unsigned* bar = b.bar;
;         __builtin_amdgcn_s_waitcnt(0);
;         unsigned nloc = b.st[0], nx = b.st[1];
;         if (nloc == 0u) { xcd_barrier_complete(bar, b.x, nloc, nx); b.st[0] = nloc; b.st[1] = nx; }
;         const unsigned old = xb_add(&bar[XB_XSUB(b.x)], 1u);
;         const unsigned gen = old / nloc;
;         if (old + 1u == (gen + 1u) * nloc) {
;             __builtin_amdgcn_fence(__ATOMIC_RELEASE, "agent");
;             asm volatile("s_waitcnt vmcnt(0)" ::: "memory");
;             const unsigned og = xb_add(&bar[XB_TOP], 1u);
;             const unsigned tg = og / nx;
;             if (og + 1u == (tg + 1u) * nx) xb_add(&bar[XB_TOPGEN], 1u);
;             else XB_SPIN(xb_ld(&bar[XB_TOPGEN]) == tg, bar);
;             __builtin_amdgcn_fence(__ATOMIC_ACQUIRE, "agent");
;             xb_add(&bar[XB_XGEN(b.x)], 1u);
;             asm volatile("s_waitcnt vmcnt(0)" ::: "memory");
;         } else {
;             XB_SPIN(xb_ld(&bar[XB_XGEN(b.x)]) == gen, bar);
;             __builtin_amdgcn_fence(__ATOMIC_ACQUIRE, "agent");
;             asm volatile("s_waitcnt vmcnt(0)" ::: "memory");
;         }
;     }
;     __syncthreads();
; }
.LBB0_404:
	v_readlane_b32 s6, v252, 34
	v_readlane_b32 s7, v252, 35
	v_mov_b32_e32 v15, 0x23080
	v_mov_b32_e32 v17, 0x80
	ds_add_rtn_u32 v17, v15, v17
	s_nop 2
	global_load_dword v16, v1, s[6:7] offset:-256 sc1
	v_mov_b32_e32 v14, 0x23084
	ds_read_b32 v14, v14
	s_waitcnt lgkmcnt(0)
	v_readfirstlane_b32 s9, v14
	s_nop 3
	s_cmp_eq_u32 s9, 0
	s_cbranch_scc1 .Lgu_full
	v_readlane_b32 s8, v252, 34
	v_readlane_b32 s9, v252, 35
	s_and_b32 s30, s2, 7
	s_lshl_b32 s30, s30, 3
	s_bfe_u32 s31, s2, 0x30003
	s_or_b32 s30, s30, s31
	s_lshl_b32 s30, s30, 5
	s_addk_i32 s30, 0x3600
	s_add_u32 s8, s8, s30
	s_addc_u32 s9, s9, 0
	v_mov_b32_e32 v14, 0x23088
	v_mov_b32_e32 v12, 4
	ds_add_rtn_u32 v13, v14, v12
	v_mov_b32_e32 v11, 1
	s_nop 1
	global_atomic_add v1, v11, s[8:9]
	buffer_inv sc1
	s_waitcnt lgkmcnt(0)
	v_add_u32_e32 v13, 4, v13
	v_add_u32_e32 v17, 0x80, v17
	s_mov_b32 s5, 0

; __device__ __forceinline__ unsigned xb_ld(unsigned* p)              { return __hip_atomic_load(p, __ATOMIC_RELAXED, __HIP_MEMORY_SCOPE_AGENT); }
; __device__ __forceinline__ unsigned xb_add(unsigned* p, unsigned v) { return __hip_atomic_fetch_add(p, v, __ATOMIC_RELAXED, __HIP_MEMORY_SCOPE_AGENT); }
; #define XB_SPIN(cond, bar) do { unsigned _sp = 0; while (cond) { __builtin_amdgcn_s_sleep(8); \
;     if ((++_sp & 255u) == 0u) { if (xb_ld(&(bar)[XB_TMO])) break; if (_sp > XB_SPIN_CAP) { atomicAdd(&(bar)[XB_TMO], 1u); break; } } } } while (0)
; __device__ __forceinline__ void xcd_barrier(const XcdBarrier& b) {
;     asm volatile("s_waitcnt vmcnt(0)" ::: "memory");
;     __syncthreads();
;     if (threadIdx.x == 0) {
;         unsigned* bar = b.bar;
;         __builtin_amdgcn_s_waitcnt(0);
;         unsigned nloc = b.st[0], nx = b.st[1];
;         if (nloc == 0u) { xcd_barrier_complete(bar, b.x, nloc, nx); b.st[0] = nloc; b.st[1] = nx; }
;         const unsigned old = xb_add(&bar[XB_XSUB(b.x)], 1u);
;         const unsigned gen = old / nloc;
;         if (old + 1u == (gen + 1u) * nloc) {
;             __builtin_amdgcn_fence(__ATOMIC_RELEASE, "agent");
;             asm volatile("s_waitcnt vmcnt(0)" ::: "memory");
;             const unsigned og = xb_add(&bar[XB_TOP], 1u);
;             const unsigned tg = og / nx;
;             if (og + 1u == (tg + 1u) * nx) xb_add(&bar[XB_TOPGEN], 1u);
;             else XB_SPIN(xb_ld(&bar[XB_TOPGEN]) == tg, bar);
;             __builtin_amdgcn_fence(__ATOMIC_ACQUIRE, "agent");
;             xb_add(&bar[XB_XGEN(b.x)], 1u);
;             asm volatile("s_waitcnt vmcnt(0)" ::: "memory");
;         } else {
;             XB_SPIN(xb_ld(&bar[XB_XGEN(b.x)]) == gen, bar);
;             __builtin_amdgcn_fence(__ATOMIC_ACQUIRE, "agent");
;             asm volatile("s_waitcnt vmcnt(0)" ::: "memory");
;         }
;     }
;     __syncthreads();
; }
.LBB0_502:
	v_mov_b32_e32 v14, 0x23084
	ds_read_b32 v14, v14
	v_readlane_b32 s4, v252, 23
	s_waitcnt lgkmcnt(0)
	v_readfirstlane_b32 s5, v14
	s_nop 3
	s_cmp_eq_u32 s5, 0
	s_cbranch_scc1 .Ld_full
	s_cmp_eq_u32 s4, 0
	s_cbranch_scc1 .Ld_first
	v_readlane_b32 s4, v252, 34
	v_readlane_b32 s5, v252, 35
	s_and_b32 s44, s2, 7
	s_lshl_b32 s44, s44, 3
	s_bfe_u32 s45, s2, 0x30003
	s_or_b32 s44, s44, s45
	s_lshl_b32 s44, s44, 5
	s_addk_i32 s44, 0x3600
	s_add_u32 s4, s4, s44
	s_addc_u32 s5, s5, 0
	v_mov_b32_e32 v14, 0x23088
	v_mov_b32_e32 v12, 4
	ds_add_rtn_u32 v13, v14, v12
	v_mov_b32_e32 v11, 1
	s_nop 1
	global_atomic_add v1, v11, s[4:5]
	buffer_inv sc1
	s_waitcnt lgkmcnt(0)
	v_add_u32_e32 v13, 4, v13
	s_mov_b32 s46, 0

; __device__ __forceinline__ unsigned xb_ld(unsigned* p)              { return __hip_atomic_load(p, __ATOMIC_RELAXED, __HIP_MEMORY_SCOPE_AGENT); }
; __device__ __forceinline__ unsigned xb_add(unsigned* p, unsigned v) { return __hip_atomic_fetch_add(p, v, __ATOMIC_RELAXED, __HIP_MEMORY_SCOPE_AGENT); }
; #define XB_SPIN(cond, bar) do { unsigned _sp = 0; while (cond) { __builtin_amdgcn_s_sleep(8); \
;     if ((++_sp & 255u) == 0u) { if (xb_ld(&(bar)[XB_TMO])) break; if (_sp > XB_SPIN_CAP) { atomicAdd(&(bar)[XB_TMO], 1u); break; } } } } while (0)
; __device__ __forceinline__ void xcd_barrier(const XcdBarrier& b) {
;     asm volatile("s_waitcnt vmcnt(0)" ::: "memory");
;     __syncthreads();
;     if (threadIdx.x == 0) {
;         unsigned* bar = b.bar;
;         __builtin_amdgcn_s_waitcnt(0);
;         unsigned nloc = b.st[0], nx = b.st[1];
;         if (nloc == 0u) { xcd_barrier_complete(bar, b.x, nloc, nx); b.st[0] = nloc; b.st[1] = nx; }
;         const unsigned old = xb_add(&bar[XB_XSUB(b.x)], 1u);
;         const unsigned gen = old / nloc;
;         if (old + 1u == (gen + 1u) * nloc) {
;             __builtin_amdgcn_fence(__ATOMIC_RELEASE, "agent");
;             asm volatile("s_waitcnt vmcnt(0)" ::: "memory");
;             const unsigned og = xb_add(&bar[XB_TOP], 1u);
;             const unsigned tg = og / nx;
;             if (og + 1u == (tg + 1u) * nx) xb_add(&bar[XB_TOPGEN], 1u);
;             else XB_SPIN(xb_ld(&bar[XB_TOPGEN]) == tg, bar);
;             __builtin_amdgcn_fence(__ATOMIC_ACQUIRE, "agent");
;             xb_add(&bar[XB_XGEN(b.x)], 1u);
;             asm volatile("s_waitcnt vmcnt(0)" ::: "memory");
;         } else {
;             XB_SPIN(xb_ld(&bar[XB_XGEN(b.x)]) == gen, bar);
;             __builtin_amdgcn_fence(__ATOMIC_ACQUIRE, "agent");
;             asm volatile("s_waitcnt vmcnt(0)" ::: "memory");
;         }
;     }
;     __syncthreads();
; }
.Ld_first:
	v_readlane_b32 s4, v252, 34
	v_readlane_b32 s5, v252, 35
	v_mov_b32_e32 v11, 1
	v_mov_b32_e32 v14, 0x23090
	v_mov_b32_e32 v12, 0x100
	ds_add_u32 v14, v12
	s_nop 0
	global_atomic_add v1, v11, s[4:5] offset:-128
	v_readlane_b32 s4, v253, 44
	v_readlane_b32 s5, v253, 45
	v_mov_b32_e32 v14, 0x2308c
	ds_add_rtn_u32 v13, v14, v3
	s_nop 2
	global_atomic_add v1, v11, s[4:5] offset:128
	buffer_inv sc1
	s_waitcnt lgkmcnt(0)
	v_add_u32_e32 v13, v13, v3
	s_mov_b32 s46, 0

; __device__ __forceinline__ unsigned xb_ld(unsigned* p)              { return __hip_atomic_load(p, __ATOMIC_RELAXED, __HIP_MEMORY_SCOPE_AGENT); }
; __device__ __forceinline__ unsigned xb_add(unsigned* p, unsigned v) { return __hip_atomic_fetch_add(p, v, __ATOMIC_RELAXED, __HIP_MEMORY_SCOPE_AGENT); }
; #define XB_SPIN(cond, bar) do { unsigned _sp = 0; while (cond) { __builtin_amdgcn_s_sleep(8); \
;     if ((++_sp & 255u) == 0u) { if (xb_ld(&(bar)[XB_TMO])) break; if (_sp > XB_SPIN_CAP) { atomicAdd(&(bar)[XB_TMO], 1u); break; } } } } while (0)
; __device__ __forceinline__ void xcd_barrier(const XcdBarrier& b) {
;     asm volatile("s_waitcnt vmcnt(0)" ::: "memory");
;     __syncthreads();
;     if (threadIdx.x == 0) {
;         unsigned* bar = b.bar;
;         __builtin_amdgcn_s_waitcnt(0);
;         unsigned nloc = b.st[0], nx = b.st[1];
;         if (nloc == 0u) { xcd_barrier_complete(bar, b.x, nloc, nx); b.st[0] = nloc; b.st[1] = nx; }
;         const unsigned old = xb_add(&bar[XB_XSUB(b.x)], 1u);
;         const unsigned gen = old / nloc;
;         if (old + 1u == (gen + 1u) * nloc) {
;             __builtin_amdgcn_fence(__ATOMIC_RELEASE, "agent");
;             asm volatile("s_waitcnt vmcnt(0)" ::: "memory");
;             const unsigned og = xb_add(&bar[XB_TOP], 1u);
;             const unsigned tg = og / nx;
;             if (og + 1u == (tg + 1u) * nx) xb_add(&bar[XB_TOPGEN], 1u);
;             else XB_SPIN(xb_ld(&bar[XB_TOPGEN]) == tg, bar);
;             __builtin_amdgcn_fence(__ATOMIC_ACQUIRE, "agent");
;             xb_add(&bar[XB_XGEN(b.x)], 1u);
;             asm volatile("s_waitcnt vmcnt(0)" ::: "memory");
;         } else {
;             XB_SPIN(xb_ld(&bar[XB_XGEN(b.x)]) == gen, bar);
;             __builtin_amdgcn_fence(__ATOMIC_ACQUIRE, "agent");
;             asm volatile("s_waitcnt vmcnt(0)" ::: "memory");
;         }
;     }
;     __syncthreads();
; }
.LBB0_1241:
	v_mov_b32_e32 v14, 0x23084
	ds_read_b32 v14, v14
	s_waitcnt lgkmcnt(0)
	v_readfirstlane_b32 s5, v14
	s_nop 3
	s_cmp_eq_u32 s5, 0
	s_cbranch_scc1 .Lout_full
	v_readlane_b32 s4, v252, 34
	v_readlane_b32 s5, v252, 35
	s_and_b32 s6, s2, 7
	s_lshl_b32 s6, s6, 3
	s_bfe_u32 s7, s2, 0x30003
	s_or_b32 s6, s6, s7
	s_lshl_b32 s6, s6, 5
	s_addk_i32 s6, 0x3600
	s_add_u32 s4, s4, s6
	s_addc_u32 s5, s5, 0
	v_mov_b32_e32 v14, 0x23088
	v_mov_b32_e32 v12, 4
	ds_add_rtn_u32 v13, v14, v12
	v_mov_b32_e32 v11, 1
	s_nop 1
	global_atomic_add v1, v11, s[4:5]
	buffer_inv sc1
	s_waitcnt lgkmcnt(0)
	v_add_u32_e32 v13, 4, v13
	s_mov_b32 s8, 0
